# attention-C key-row loop: wait for the loop-invariant Q loads once before the loop instead of a vmcnt(3..0) ladder inside it that also drained the next row's prefetch
# speedup vs baseline: 1.0738x; 1.0100x over previous
.LBB0_513:
	s_and_b32 s4, s4, 0x3fffffc0
	v_and_b32_e32 v130, 63, v0
	s_lshl_b32 s4, s4, 2
	v_med3_u32 v0, s5, 1, 57
	s_add_i32 s79, s4, 0
	v_readfirstlane_b32 s4, v0
	s_add_i32 s79, s79, 0x20000
	s_sub_i32 s87, s4, s9
	v_mov_b32_e32 v15, 0
	s_cmp_lt_i32 s87, -6
	v_cmp_gt_u32_e64 s[4:5], 32, v130
	v_lshl_add_u32 v131, v128, 2, s79
	v_mov_b32_e32 v14, v15
	v_mov_b32_e32 v13, v15
	v_mov_b32_e32 v12, v15
	v_mov_b32_e32 v11, v15
	v_mov_b32_e32 v10, v15
	v_mov_b32_e32 v9, v15
	v_mov_b32_e32 v8, v15
	v_mov_b32_e32 v7, v15
	v_mov_b32_e32 v6, v15
	v_mov_b32_e32 v5, v15
	v_mov_b32_e32 v4, v15
	v_mov_b32_e32 v3, v15
	v_mov_b32_e32 v2, v15
	v_mov_b32_e32 v1, v15
	v_mov_b32_e32 v0, v15
	v_mov_b32_e32 v31, v15
	v_mov_b32_e32 v30, v15
	v_mov_b32_e32 v29, v15
	v_mov_b32_e32 v28, v15
	v_mov_b32_e32 v27, v15
	v_mov_b32_e32 v26, v15
	v_mov_b32_e32 v25, v15
	v_mov_b32_e32 v24, v15
	v_mov_b32_e32 v23, v15
	v_mov_b32_e32 v22, v15
	v_mov_b32_e32 v21, v15
	v_mov_b32_e32 v20, v15
	v_mov_b32_e32 v19, v15
	v_mov_b32_e32 v18, v15
	v_mov_b32_e32 v17, v15
	v_mov_b32_e32 v16, v15
	v_mov_b32_e32 v176, v15
	s_cbranch_scc1 .LBB0_527
	v_mov_b32_e32 v121, v195
	v_lshl_add_u64 v[124:125], s[0:1], 0, v[120:121]
	s_bfe_u32 s0, s3, 0x40002
	s_lshl_b32 s1, s0, 2
	s_min_u32 s88, s1, 4
	v_med3_u32 v3, s1, 1, 57
	v_lshl_add_u64 v[122:123], s[6:7], 0, v[120:121]
	s_sub_i32 s86, s1, s88
	s_and_b32 s89, s75, 0xfffff000
	s_lshl_b32 s73, s0, 8
	s_lshl_b32 s72, s88, 6
	v_add_u32_e32 v121, 7, v3
	s_add_i32 s87, s87, 7
	v_med3_i32 v3, s8, 4, 60
	s_add_i32 s0, 0, 0x4000
	v_add_u32_e32 v134, -4, v3
	v_med3_u32 v4, v33, 8, 56
	v_add_u32_e32 v135, 4, v3
	v_and_b32_e32 v3, 0x70, v34
	s_cmp_lg_u32 s0, -1
	v_lshlrev_b32_e32 v6, 2, v129
	v_add_u32_e32 v5, -8, v4
	s_cselect_b32 s0, s0, 0
	v_bitop3_b32 v138, v194, v3, 32 bitop3:0x36
	v_bitop3_b32 v139, v194, v3, 64 bitop3:0x36
	v_bitop3_b32 v140, v194, v3, s62 bitop3:0x36
	v_or_b32_e32 v3, 32, v6
	v_or_b32_e32 v8, 24, v6
	v_or_b32_e32 v9, 1, v6
	v_lshl_add_u32 v136, v128, 7, s0
	v_cmp_ge_u32_e32 vcc, v3, v5
	v_cmp_lt_u32_e64 s[0:1], v8, v4
	v_or_b32_e32 v10, 33, v6
	v_cmp_lt_u32_e64 s[10:11], v9, v5
	v_or_b32_e32 v9, 25, v6
	v_or_b32_e32 v11, 2, v6
	s_and_b64 s[8:9], vcc, s[0:1]
	v_cmp_ge_u32_e32 vcc, v10, v5
	v_cmp_lt_u32_e64 s[0:1], v9, v4
	v_or_b32_e32 v12, 34, v6
	v_cmp_lt_u32_e64 s[14:15], v11, v5
	v_or_b32_e32 v11, 26, v6
	v_or_b32_e32 v13, 3, v6
	s_and_b64 s[12:13], vcc, s[0:1]
	v_cmp_ge_u32_e32 vcc, v12, v5
	v_cmp_lt_u32_e64 s[0:1], v11, v4
	v_or_b32_e32 v14, 35, v6
	v_cmp_lt_u32_e64 s[18:19], v13, v5
	v_or_b32_e32 v13, 27, v6
	s_and_b64 s[16:17], vcc, s[0:1]
	v_cmp_ge_u32_e32 vcc, v14, v5
	v_cmp_lt_u32_e64 s[0:1], v13, v4
	v_or_b32_e32 v15, 8, v6
	v_or_b32_e32 v16, 40, v6
	s_and_b64 s[20:21], vcc, s[0:1]
	v_cmp_lt_u32_e64 s[22:23], v15, v5
	v_cmp_ge_u32_e32 vcc, v16, v5
	v_cmp_lt_u32_e64 s[0:1], v3, v4
	v_or_b32_e32 v3, 9, v6
	v_or_b32_e32 v15, 41, v6
	s_and_b64 s[24:25], vcc, s[0:1]
	v_cmp_lt_u32_e64 s[26:27], v3, v5
	v_cmp_ge_u32_e32 vcc, v15, v5
	v_cmp_lt_u32_e64 s[0:1], v10, v4
	v_or_b32_e32 v3, 10, v6
	v_or_b32_e32 v10, 42, v6
	s_and_b64 s[28:29], vcc, s[0:1]
	v_cmp_lt_u32_e64 s[30:31], v3, v5
	v_cmp_ge_u32_e32 vcc, v10, v5
	v_cmp_lt_u32_e64 s[0:1], v12, v4
	v_or_b32_e32 v3, 11, v6
	v_or_b32_e32 v12, 43, v6
	v_add_u32_e32 v7, 8, v4
	s_and_b64 s[34:35], vcc, s[0:1]
	v_cmp_lt_u32_e64 s[36:37], v3, v5
	v_cmp_ge_u32_e32 vcc, v12, v5
	v_cmp_lt_u32_e64 s[0:1], v14, v4
	v_or_b32_e32 v3, 16, v6
	s_and_b64 s[38:39], vcc, s[0:1]
	v_cmp_ge_u32_e32 vcc, v3, v5
	v_cmp_lt_u32_e64 s[0:1], v3, v7
	v_or_b32_e32 v3, 17, v6
	v_bitop3_b32 v137, v194, v34, s41 bitop3:0x78
	s_and_b64 s[40:41], vcc, s[0:1]
	v_cmp_ge_u32_e32 vcc, v3, v5
	v_cmp_lt_u32_e64 s[0:1], v3, v7
	v_or_b32_e32 v3, 18, v6
	s_and_b64 s[44:45], vcc, s[0:1]
	v_cmp_ge_u32_e32 vcc, v3, v5
	v_cmp_lt_u32_e64 s[0:1], v3, v7
	v_or_b32_e32 v3, 19, v6
	s_and_b64 s[48:49], vcc, s[0:1]
	v_cmp_ge_u32_e32 vcc, v3, v5
	v_cmp_lt_u32_e64 s[0:1], v3, v7
	s_and_b64 s[52:53], vcc, s[0:1]
	v_cmp_ge_u32_e32 vcc, v8, v5
	v_cmp_lt_u32_e64 s[0:1], v8, v7
	s_and_b64 s[56:57], vcc, s[0:1]
	v_cmp_ge_u32_e32 vcc, v9, v5
	v_cmp_lt_u32_e64 s[0:1], v9, v7
	s_and_b64 s[60:61], vcc, s[0:1]
	v_cmp_ge_u32_e32 vcc, v11, v5
	v_cmp_lt_u32_e64 s[0:1], v11, v7
	s_and_b64 s[64:65], vcc, s[0:1]
	v_cmp_ge_u32_e32 vcc, v13, v5
	v_cmp_lt_u32_e64 s[0:1], v13, v7
	s_mov_b32 s84, s68
	v_lshlrev_b32_e32 v2, 1, v130
	s_and_b64 s[68:69], vcc, s[0:1]
	v_lshlrev_b32_e32 v0, 3, v130
	v_lshlrev_b32_e32 v1, 4, v130
	v_and_b32_e32 v2, 32, v2
	s_movk_i32 s0, 0x118
	s_cmp_lg_u32 0, -1
	v_and_b32_e32 v1, 0xc0, v1
	v_and_or_b32 v0, v0, s0, v2
	s_cselect_b32 s0, 0, 0
	v_add3_u32 v141, v1, s0, v0
	v_sub_u32_e32 v0, v6, v128
	v_subrev_u32_e32 v0, s81, v0
	v_add_u32_e32 v1, 59, v0
	v_min_i32_e32 v1, 15, v1
	v_lshl_add_u32 v142, v1, 2, v234
	v_add_u32_e32 v1, 27, v0
	v_med3_i32 v1, v1, -15, 15
	v_lshl_add_u32 v143, v1, 2, v234
	v_add_u32_e32 v1, 58, v0
	v_min_i32_e32 v1, 15, v1
	v_lshl_add_u32 v144, v1, 2, v234
	v_add_u32_e32 v1, 26, v0
	v_med3_i32 v1, v1, -15, 15
	v_lshl_add_u32 v145, v1, 2, v234
	v_add_u32_e32 v1, 57, v0
	v_min_i32_e32 v1, 15, v1
	v_lshl_add_u32 v146, v1, 2, v234
	v_add_u32_e32 v1, 25, v0
	v_med3_i32 v1, v1, -15, 15
	v_lshl_add_u32 v147, v1, 2, v234
	v_add_u32_e32 v1, 56, v0
	v_min_i32_e32 v1, 15, v1
	v_lshl_add_u32 v148, v1, 2, v234
	v_add_u32_e32 v1, 24, v0
	v_med3_i32 v1, v1, -15, 15
	v_lshl_add_u32 v149, v1, 2, v234
	v_add_u32_e32 v1, 51, v0
	v_min_i32_e32 v1, 15, v1
	v_lshl_add_u32 v150, v1, 2, v234
	v_add_u32_e32 v1, 19, v0
	v_med3_i32 v1, v1, -15, 15
	v_lshl_add_u32 v151, v1, 2, v234
	v_add_u32_e32 v1, 50, v0
	v_min_i32_e32 v1, 15, v1
	v_lshl_add_u32 v152, v1, 2, v234
	v_add_u32_e32 v1, 18, v0
	v_med3_i32 v1, v1, -15, 15
	v_lshl_add_u32 v153, v1, 2, v234
	v_add_u32_e32 v1, 49, v0
	v_min_i32_e32 v1, 15, v1
	v_lshl_add_u32 v154, v1, 2, v234
	v_add_u32_e32 v1, 17, v0
	v_med3_i32 v1, v1, -15, 15
	v_lshl_add_u32 v155, v1, 2, v234
	v_add_u32_e32 v1, 48, v0
	v_min_i32_e32 v1, 15, v1
	v_lshl_add_u32 v156, v1, 2, v234
	v_add_u32_e32 v1, 16, v0
	v_med3_i32 v1, v1, -15, 15
	v_lshl_add_u32 v157, v1, 2, v234
	v_add_u32_e32 v1, 43, v0
	v_med3_i32 v1, v1, -15, 15
	v_lshl_add_u32 v158, v1, 2, v234
	v_add_u32_e32 v1, 11, v0
	v_max_i32_e32 v1, -15, v1
	v_lshl_add_u32 v159, v1, 2, v234
	v_add_u32_e32 v1, 42, v0
	v_med3_i32 v1, v1, -15, 15
	v_lshl_add_u32 v160, v1, 2, v234
	v_add_u32_e32 v1, 10, v0
	v_max_i32_e32 v1, -15, v1
	v_lshl_add_u32 v161, v1, 2, v234
	v_add_u32_e32 v1, 41, v0
	v_med3_i32 v1, v1, -15, 15
	v_lshl_add_u32 v162, v1, 2, v234
	v_add_u32_e32 v1, 9, v0
	v_max_i32_e32 v1, -15, v1
	v_lshl_add_u32 v163, v1, 2, v234
	v_add_u32_e32 v1, 40, v0
	v_med3_i32 v1, v1, -15, 15
	v_lshl_add_u32 v164, v1, 2, v234
	v_add_u32_e32 v1, 8, v0
	v_max_i32_e32 v1, -15, v1
	v_lshl_add_u32 v165, v1, 2, v234
	v_add_u32_e32 v1, 35, v0
	v_med3_i32 v1, v1, -15, 15
	v_lshl_add_u32 v166, v1, 2, v234
	v_add_u32_e32 v1, 3, v0
	v_max_i32_e32 v1, -15, v1
	v_lshl_add_u32 v167, v1, 2, v234
	v_add_u32_e32 v1, 34, v0
	v_med3_i32 v1, v1, -15, 15
	v_lshl_add_u32 v168, v1, 2, v234
	v_add_u32_e32 v1, 2, v0
	v_max_i32_e32 v1, -15, v1
	v_lshl_add_u32 v169, v1, 2, v234
	v_add_u32_e32 v1, 33, v0
	v_med3_i32 v1, v1, -15, 15
	s_add_i32 s0, s80, s88
	v_lshl_add_u32 v170, v1, 2, v234
	v_add_u32_e32 v1, 1, v0
	s_mulk_i32 s0, 0xff84
	v_max_i32_e32 v1, -15, v1
	s_add_i32 s88, s0, 0
	v_lshl_add_u32 v171, v1, 2, v234
	v_add_u32_e32 v1, 32, v0
	v_max_i32_e32 v0, -15, v0
	s_or_b32 s0, s73, s89
	v_lshl_add_u32 v173, v0, 2, v234
	v_add_u32_e32 v0, s0, v32
	v_or_b32_e32 v14, 48, v6
	v_cmp_lt_u32_e64 s[42:43], v16, v4
	v_or_b32_e32 v16, 49, v6
	v_cmp_lt_u32_e64 s[46:47], v15, v4
	v_or_b32_e32 v15, 50, v6
	v_cmp_lt_u32_e64 s[50:51], v10, v4
	v_or_b32_e32 v10, 51, v6
	v_med3_i32 v1, v1, -15, 15
	v_subrev_u32_e32 v0, s72, v0
	v_mov_b32_e32 v176, 0
	s_mov_b32 s85, 0x42800000
	s_mov_b32 s90, 1
	v_cmp_lt_u32_e64 s[6:7], v6, v5
	v_cmp_lt_u32_e64 s[54:55], v12, v4
	v_cmp_lt_u32_e64 s[58:59], v14, v4
	v_cmp_lt_u32_e64 s[62:63], v16, v4
	v_cmp_lt_u32_e64 s[66:67], v15, v4
	v_cmp_lt_u32_e64 s[70:71], v10, v4
	v_lshl_add_u32 v172, v1, 2, v234
	v_add_u32_e32 v174, 64, v0
	v_mov_b32_e32 v175, 0xf149f2ca
	v_mov_b32_e32 v16, 0
	v_mov_b32_e32 v17, v176
	v_mov_b32_e32 v18, v176
	v_mov_b32_e32 v19, v176
	v_mov_b32_e32 v20, v176
	v_mov_b32_e32 v21, v176
	v_mov_b32_e32 v22, v176
	v_mov_b32_e32 v23, v176
	v_mov_b32_e32 v24, v176
	v_mov_b32_e32 v25, v176
	v_mov_b32_e32 v26, v176
	v_mov_b32_e32 v27, v176
	v_mov_b32_e32 v28, v176
	v_mov_b32_e32 v29, v176
	v_mov_b32_e32 v30, v176
	v_mov_b32_e32 v31, v176
	v_mov_b32_e32 v0, v176
	v_mov_b32_e32 v1, v176
	v_mov_b32_e32 v2, v176
	v_mov_b32_e32 v3, v176
	v_mov_b32_e32 v4, v176
	v_mov_b32_e32 v5, v176
	v_mov_b32_e32 v6, v176
	v_mov_b32_e32 v7, v176
	v_mov_b32_e32 v8, v176
	v_mov_b32_e32 v9, v176
	v_mov_b32_e32 v10, v176
	v_mov_b32_e32 v11, v176
	v_mov_b32_e32 v12, v176
	v_mov_b32_e32 v13, v176
	v_mov_b32_e32 v14, v176
	v_mov_b32_e32 v15, v176
	s_waitcnt vmcnt(0)
	s_branch .LBB0_516

.LBB0_518:
	v_cmp_ge_i32_e32 vcc, s86, v134
	v_cmp_lt_u32_e64 s[0:1], s86, v135
	s_add_i32 s72, s90, -1
	s_and_b64 s[0:1], vcc, s[0:1]
	s_andn2_b64 vcc, exec, s[0:1]
	s_and_b32 s89, s72, 1
	s_cbranch_vccnz .LBB0_524
	s_lshl_b32 s0, s89, 13
	v_add_u32_e32 v40, s0, v136
	v_add_u32_e32 v41, v40, v137
	ds_read_b128 v[32:35], v41 offset:0
	ds_read_b128 v[36:39], v41 offset:0x1000
	v_add_u32_e32 v41, v40, v138
	ds_read_b128 v[88:91], v41 offset:0
	ds_read_b128 v[92:95], v41 offset:0x1000
	v_add_u32_e32 v41, v40, v139
	ds_read_b128 v[96:99], v41 offset:0
	ds_read_b128 v[100:103], v41 offset:0x1000
	v_add_u32_e32 v40, v40, v140
	ds_read_b128 v[104:107], v40 offset:0
	ds_read_b128 v[108:111], v40 offset:0x1000
	s_waitcnt lgkmcnt(0)
	v_mfma_f32_32x32x16_bf16 v[48:63], v[32:35], v[64:67], 0
	v_mfma_f32_32x32x16_bf16 v[32:47], v[36:39], v[64:67], 0
	v_mfma_f32_32x32x16_bf16 v[48:63], v[88:91], v[68:71], v[48:63]
	v_mfma_f32_32x32x16_bf16 v[32:47], v[92:95], v[68:71], v[32:47]
	v_mfma_f32_32x32x16_bf16 v[48:63], v[96:99], v[72:75], v[48:63]
	v_mfma_f32_32x32x16_bf16 v[32:47], v[100:103], v[72:75], v[32:47]
	v_mfma_f32_32x32x16_bf16 v[48:63], v[104:107], v[80:83], v[48:63]
	v_mfma_f32_32x32x16_bf16 v[32:47], v[108:111], v[80:83], v[32:47]
	v_add_u32_e32 v177, s0, v141
	ds_read_b64_tr_b16 v[116:117], v177 offset:0
	ds_read_b64_tr_b16 v[118:119], v177 offset:0x400
	ds_read_b64_tr_b16 v[104:105], v177 offset:0x800
	ds_read_b64_tr_b16 v[106:107], v177 offset:0xc00
	ds_read_b64_tr_b16 v[96:97], v177 offset:0x1000
	ds_read_b64_tr_b16 v[98:99], v177 offset:0x1400
	ds_read_b64_tr_b16 v[92:93], v177 offset:0x1800
	ds_read_b64_tr_b16 v[94:95], v177 offset:0x1c00
	ds_read_b64_tr_b16 v[112:113], v177 offset:0x200
	ds_read_b64_tr_b16 v[114:115], v177 offset:0x600
	ds_read_b64_tr_b16 v[108:109], v177 offset:0xa00
	ds_read_b64_tr_b16 v[110:111], v177 offset:0xe00
	ds_read_b64_tr_b16 v[100:101], v177 offset:0x1200
	ds_read_b64_tr_b16 v[102:103], v177 offset:0x1600
	ds_read_b64_tr_b16 v[88:89], v177 offset:0x1a00
	ds_read_b64_tr_b16 v[90:91], v177 offset:0x1e00
	v_add_u32_e32 v177, s88, v173
	ds_read_b32 v177, v177
	v_add_u32_e32 v178, s88, v172
	ds_read_b32 v178, v178
	s_waitcnt lgkmcnt(1)
	s_nop 4
	v_add_f32_e32 v48, v48, v177
	v_add_u32_e32 v177, s88, v171
	ds_read_b32 v177, v177
	s_waitcnt lgkmcnt(1)
	v_add_f32_e32 v32, v32, v178
	v_add_u32_e32 v178, s88, v170
	ds_read_b32 v178, v178
	v_cndmask_b32_e64 v48, v48, v232, s[6:7]
	s_waitcnt lgkmcnt(1)
	v_add_f32_e32 v49, v49, v177
	v_add_u32_e32 v177, s88, v169
	ds_read_b32 v177, v177
	s_waitcnt lgkmcnt(1)
	v_add_f32_e32 v33, v33, v178
	v_add_u32_e32 v178, s88, v168
	ds_read_b32 v178, v178
	v_cndmask_b32_e64 v49, v49, v232, s[10:11]
	s_waitcnt lgkmcnt(1)
	v_add_f32_e32 v50, v50, v177
	v_add_u32_e32 v177, s88, v167
	ds_read_b32 v177, v177
	s_waitcnt lgkmcnt(1)
	v_add_f32_e32 v34, v34, v178
	v_add_u32_e32 v178, s88, v166
	ds_read_b32 v178, v178
	v_cndmask_b32_e64 v50, v50, v232, s[14:15]
	s_waitcnt lgkmcnt(1)
	v_add_f32_e32 v51, v51, v177
	v_add_u32_e32 v177, s88, v165
	ds_read_b32 v177, v177
	s_waitcnt lgkmcnt(1)
	v_add_f32_e32 v35, v35, v178
	v_add_u32_e32 v178, s88, v164
	ds_read_b32 v178, v178
	v_cndmask_b32_e64 v51, v51, v232, s[18:19]
	s_waitcnt lgkmcnt(1)
	v_add_f32_e32 v52, v52, v177
	v_add_u32_e32 v177, s88, v163
	ds_read_b32 v177, v177
	s_waitcnt lgkmcnt(1)
	v_add_f32_e32 v36, v36, v178
	v_add_u32_e32 v178, s88, v162
	ds_read_b32 v178, v178
	v_cndmask_b32_e64 v52, v52, v232, s[22:23]
	s_waitcnt lgkmcnt(1)
	v_add_f32_e32 v53, v53, v177
	v_add_u32_e32 v177, s88, v161
	ds_read_b32 v177, v177
	s_waitcnt lgkmcnt(1)
	v_add_f32_e32 v37, v37, v178
	v_add_u32_e32 v178, s88, v160
	ds_read_b32 v178, v178
	v_cndmask_b32_e64 v53, v53, v232, s[26:27]
	s_waitcnt lgkmcnt(1)
	v_add_f32_e32 v54, v54, v177
	v_add_u32_e32 v177, s88, v159
	ds_read_b32 v177, v177
	s_waitcnt lgkmcnt(1)
	v_add_f32_e32 v38, v38, v178
	v_add_u32_e32 v178, s88, v158
	ds_read_b32 v178, v178
	v_cndmask_b32_e64 v54, v54, v232, s[30:31]
	s_waitcnt lgkmcnt(1)
	v_add_f32_e32 v55, v55, v177
	v_add_u32_e32 v177, s88, v157
	ds_read_b32 v177, v177
	s_waitcnt lgkmcnt(1)
	v_add_f32_e32 v39, v39, v178
	v_add_u32_e32 v178, s88, v156
	ds_read_b32 v178, v178
	v_cndmask_b32_e64 v55, v55, v232, s[36:37]
	s_waitcnt lgkmcnt(1)
	v_add_f32_e32 v56, v56, v177
	v_add_u32_e32 v177, s88, v155
	ds_read_b32 v177, v177
	s_waitcnt lgkmcnt(1)
	v_add_f32_e32 v40, v40, v178
	v_add_u32_e32 v178, s88, v154
	ds_read_b32 v178, v178
	v_cndmask_b32_e64 v56, v232, v56, s[40:41]
	s_waitcnt lgkmcnt(1)
	v_add_f32_e32 v57, v57, v177
	v_add_u32_e32 v177, s88, v153
	ds_read_b32 v177, v177
	s_waitcnt lgkmcnt(1)
	v_add_f32_e32 v41, v41, v178
	v_add_u32_e32 v178, s88, v152
	ds_read_b32 v178, v178
	v_cndmask_b32_e64 v57, v232, v57, s[44:45]
	s_waitcnt lgkmcnt(1)
	v_add_f32_e32 v58, v58, v177
	v_add_u32_e32 v177, s88, v151
	ds_read_b32 v177, v177
	s_waitcnt lgkmcnt(1)
	v_add_f32_e32 v42, v42, v178
	v_add_u32_e32 v178, s88, v150
	ds_read_b32 v178, v178
	v_cndmask_b32_e64 v58, v232, v58, s[48:49]
	s_waitcnt lgkmcnt(1)
	v_add_f32_e32 v59, v59, v177
	v_add_u32_e32 v177, s88, v149
	ds_read_b32 v177, v177
	s_waitcnt lgkmcnt(1)
	v_add_f32_e32 v43, v43, v178
	v_add_u32_e32 v178, s88, v148
	ds_read_b32 v178, v178
	v_cndmask_b32_e64 v59, v232, v59, s[52:53]
	s_waitcnt lgkmcnt(1)
	v_add_f32_e32 v60, v60, v177
	v_add_u32_e32 v177, s88, v147
	ds_read_b32 v177, v177
	s_waitcnt lgkmcnt(1)
	v_add_f32_e32 v44, v44, v178
	v_add_u32_e32 v178, s88, v146
	ds_read_b32 v178, v178
	v_cndmask_b32_e64 v60, v232, v60, s[56:57]
	s_waitcnt lgkmcnt(1)
	v_add_f32_e32 v61, v61, v177
	v_add_u32_e32 v177, s88, v145
	ds_read_b32 v177, v177
	s_waitcnt lgkmcnt(1)
	v_add_f32_e32 v45, v45, v178
	v_add_u32_e32 v178, s88, v144
	ds_read_b32 v178, v178
	v_cndmask_b32_e64 v61, v232, v61, s[60:61]
	s_waitcnt lgkmcnt(1)
	v_add_f32_e32 v62, v62, v177
	v_add_u32_e32 v177, s88, v143
	ds_read_b32 v177, v177
	s_waitcnt lgkmcnt(1)
	v_add_f32_e32 v46, v46, v178
	v_add_u32_e32 v178, s88, v142
	ds_read_b32 v178, v178
	v_cndmask_b32_e64 v62, v232, v62, s[64:65]
	s_waitcnt lgkmcnt(1)
	v_add_f32_e32 v63, v63, v177
	v_max_f32_e32 v177, v48, v49
	v_max3_f32 v177, v177, v50, v51
	v_max3_f32 v177, v177, v52, v53
	v_max3_f32 v177, v177, v54, v55
	v_max3_f32 v177, v177, v56, v57
	v_max3_f32 v177, v177, v58, v59
	v_cndmask_b32_e64 v63, v232, v63, s[68:69]
	v_max3_f32 v177, v177, v60, v61
	v_cndmask_b32_e64 v32, v232, v32, s[8:9]
	v_cndmask_b32_e64 v33, v232, v33, s[12:13]
	v_max3_f32 v177, v177, v62, v63
	v_cndmask_b32_e64 v34, v232, v34, s[16:17]
	v_cndmask_b32_e64 v35, v232, v35, s[20:21]
	v_max3_f32 v177, v177, v32, v33
	v_cndmask_b32_e64 v36, v232, v36, s[24:25]
	v_cndmask_b32_e64 v37, v232, v37, s[28:29]
	v_max3_f32 v177, v177, v34, v35
	v_cndmask_b32_e64 v38, v232, v38, s[34:35]
	v_cndmask_b32_e64 v39, v232, v39, s[38:39]
	v_max3_f32 v177, v177, v36, v37
	v_cndmask_b32_e64 v40, v232, v40, s[42:43]
	v_cndmask_b32_e64 v41, v232, v41, s[46:47]
	v_max3_f32 v177, v177, v38, v39
	v_cndmask_b32_e64 v42, v232, v42, s[50:51]
	v_cndmask_b32_e64 v43, v232, v43, s[54:55]
	v_max3_f32 v177, v177, v40, v41
	v_cndmask_b32_e64 v44, v232, v44, s[58:59]
	v_cndmask_b32_e64 v45, v232, v45, s[62:63]
	s_waitcnt lgkmcnt(0)
	v_add_f32_e32 v47, v47, v178
	v_max3_f32 v177, v177, v42, v43
	v_cndmask_b32_e64 v46, v232, v46, s[66:67]
	v_cndmask_b32_e64 v47, v232, v47, s[70:71]
	v_max3_f32 v177, v177, v44, v45
	v_max3_f32 v177, v177, v46, v47
	v_mov_b32_e32 v178, v177
	s_nop 1
	v_permlane32_swap_b32_e32 v177, v178
	v_max_f32_e32 v178, v178, v178
	v_max_f32_e32 v177, v177, v177
	v_max_f32_e32 v177, v177, v178
	v_sub_f32_e32 v178, v177, v175
	v_cmp_ge_f32_e32 vcc, s85, v178
	s_cmp_eq_u64 vcc, exec
	v_max_f32_e32 v178, v175, v175
	s_cselect_b64 vcc, -1, 0
	v_max_f32_e32 v177, v178, v177
	v_sub_f32_e32 v178, v175, v177
	v_cndmask_b32_e32 v175, v177, v175, vcc
	v_mul_f32_e32 v177, 0xbe38aa3b, v175
	v_fmamk_f32 v48, v48, 0x3e38aa3b, v177
	v_exp_f32_e32 v179, v48
	v_fmamk_f32 v49, v49, 0x3e38aa3b, v177
	v_exp_f32_e32 v180, v49
	v_fmamk_f32 v49, v50, 0x3e38aa3b, v177
	v_exp_f32_e32 v181, v49
	v_fmamk_f32 v49, v51, 0x3e38aa3b, v177
	v_exp_f32_e32 v51, v49
	v_fmamk_f32 v49, v52, 0x3e38aa3b, v177
	v_add_f32_e32 v48, 0, v179
	v_exp_f32_e32 v52, v49
	v_fmamk_f32 v49, v53, 0x3e38aa3b, v177
	v_add_f32_e32 v48, v180, v48
	v_exp_f32_e32 v53, v49
	v_fmamk_f32 v49, v54, 0x3e38aa3b, v177
	v_add_f32_e32 v48, v181, v48
	v_exp_f32_e32 v54, v49
	v_fmamk_f32 v49, v55, 0x3e38aa3b, v177
	v_add_f32_e32 v48, v51, v48
	v_exp_f32_e32 v55, v49
	v_fmamk_f32 v49, v56, 0x3e38aa3b, v177
	v_add_f32_e32 v48, v52, v48
	v_exp_f32_e32 v56, v49
	v_fmamk_f32 v49, v57, 0x3e38aa3b, v177
	v_add_f32_e32 v48, v53, v48
	v_exp_f32_e32 v57, v49
	v_fmamk_f32 v49, v58, 0x3e38aa3b, v177
	v_add_f32_e32 v48, v54, v48
	v_exp_f32_e32 v58, v49
	v_fmamk_f32 v49, v59, 0x3e38aa3b, v177
	v_add_f32_e32 v48, v55, v48
	v_exp_f32_e32 v59, v49
	v_fmamk_f32 v49, v60, 0x3e38aa3b, v177
	v_add_f32_e32 v48, v56, v48
	v_exp_f32_e32 v60, v49
	v_fmamk_f32 v49, v61, 0x3e38aa3b, v177
	v_add_f32_e32 v48, v57, v48
	v_exp_f32_e32 v61, v49
	v_fmamk_f32 v49, v62, 0x3e38aa3b, v177
	v_add_f32_e32 v48, v58, v48
	v_exp_f32_e32 v62, v49
	v_fmamk_f32 v49, v63, 0x3e38aa3b, v177
	v_add_f32_e32 v48, v59, v48
	v_exp_f32_e32 v63, v49
	v_fmamk_f32 v32, v32, 0x3e38aa3b, v177
	v_add_f32_e32 v48, v60, v48
	v_exp_f32_e32 v32, v32
	v_fmamk_f32 v33, v33, 0x3e38aa3b, v177
	v_add_f32_e32 v48, v61, v48
	v_exp_f32_e32 v33, v33
	v_fmamk_f32 v34, v34, 0x3e38aa3b, v177
	v_add_f32_e32 v48, v62, v48
	v_exp_f32_e32 v34, v34
	v_fmamk_f32 v35, v35, 0x3e38aa3b, v177
	v_add_f32_e32 v48, v63, v48
	v_exp_f32_e32 v35, v35
	v_fmamk_f32 v36, v36, 0x3e38aa3b, v177
	v_add_f32_e32 v48, v32, v48
	v_exp_f32_e32 v182, v36
	v_fmamk_f32 v37, v37, 0x3e38aa3b, v177
	v_add_f32_e32 v48, v33, v48
	v_exp_f32_e32 v183, v37
	v_fmamk_f32 v37, v38, 0x3e38aa3b, v177
	v_add_f32_e32 v48, v34, v48
	v_exp_f32_e32 v184, v37
	v_fmamk_f32 v37, v39, 0x3e38aa3b, v177
	v_add_f32_e32 v48, v35, v48
	v_exp_f32_e32 v39, v37
	v_fmamk_f32 v37, v40, 0x3e38aa3b, v177
	v_add_f32_e32 v36, v182, v48
	v_exp_f32_e32 v185, v37
	v_fmamk_f32 v37, v41, 0x3e38aa3b, v177
	v_add_f32_e32 v36, v183, v36
	v_exp_f32_e32 v186, v37
	v_fmamk_f32 v37, v42, 0x3e38aa3b, v177
	v_add_f32_e32 v36, v184, v36
	v_exp_f32_e32 v187, v37
	v_fmamk_f32 v37, v43, 0x3e38aa3b, v177
	v_add_f32_e32 v36, v39, v36
	v_exp_f32_e32 v188, v37
	v_fmamk_f32 v37, v44, 0x3e38aa3b, v177
	v_add_f32_e32 v36, v185, v36
	v_exp_f32_e32 v189, v37
	v_fmamk_f32 v37, v45, 0x3e38aa3b, v177
	v_add_f32_e32 v36, v186, v36
	v_exp_f32_e32 v190, v37
	v_fmamk_f32 v37, v46, 0x3e38aa3b, v177
	v_add_f32_e32 v36, v187, v36
	v_exp_f32_e32 v191, v37
	v_fmac_f32_e32 v177, 0x3e38aa3b, v47
	v_mul_f32_e32 v178, 0x3e38aa3b, v178
	v_add_f32_e32 v36, v188, v36
	v_exp_f32_e32 v177, v177
	v_exp_f32_e32 v178, v178
	v_add_f32_e32 v36, v189, v36
	v_add_f32_e32 v36, v190, v36
	v_add_f32_e32 v36, v191, v36
	v_add_f32_e32 v49, v177, v36
	v_cndmask_b32_e64 v48, v178, 1.0, vcc
	v_mov_b32_e32 v50, v49
	v_cvt_pk_bf16_f32 v44, v179, v180
	v_cvt_pk_bf16_f32 v45, v181, v51
	v_cvt_pk_bf16_f32 v46, v52, v53
	v_cvt_pk_bf16_f32 v47, v54, v55
	v_cvt_pk_bf16_f32 v40, v56, v57
	v_cvt_pk_bf16_f32 v41, v58, v59
	v_cvt_pk_bf16_f32 v42, v60, v61
	v_cvt_pk_bf16_f32 v43, v62, v63
	v_cvt_pk_bf16_f32 v36, v32, v33
	v_cvt_pk_bf16_f32 v37, v34, v35
	v_cvt_pk_bf16_f32 v38, v182, v183
	v_cvt_pk_bf16_f32 v39, v184, v39
	v_cvt_pk_bf16_f32 v32, v185, v186
	v_cvt_pk_bf16_f32 v33, v187, v188
	v_cvt_pk_bf16_f32 v34, v189, v190
	v_cvt_pk_bf16_f32 v35, v191, v177
	s_nop 1
	v_permlane32_swap_b32_e32 v49, v50
	v_permlane32_swap_b32_e32 v44, v46
	v_permlane32_swap_b32_e32 v45, v47
	v_permlane32_swap_b32_e32 v40, v42
	v_permlane32_swap_b32_e32 v41, v43
	v_permlane32_swap_b32_e32 v36, v38
	v_permlane32_swap_b32_e32 v37, v39
	v_permlane32_swap_b32_e32 v32, v34
	v_permlane32_swap_b32_e32 v33, v35
	v_cmp_gt_f32_e32 vcc, 1.0, v48
	s_cbranch_vccz .LBB0_523
	s_and_saveexec_b64 s[0:1], s[4:5]
	ds_write_b32 v131, v48 offset:128
	s_or_b64 exec, exec, s[0:1]
	s_waitcnt lgkmcnt(0)
	v_add_u32_e32 v51, s79, v194
	ds_read_b128 v[52:55], v51 offset:224
	ds_read_b128 v[56:59], v51 offset:192
	ds_read_b128 v[60:63], v51 offset:160
	ds_read_b128 v[178:181], v51 offset:128
	s_waitcnt lgkmcnt(3)
	v_pk_mul_f32 v[12:13], v[12:13], v[52:53]
	s_waitcnt lgkmcnt(2)
	v_pk_mul_f32 v[8:9], v[8:9], v[56:57]
	s_waitcnt lgkmcnt(1)
	v_pk_mul_f32 v[4:5], v[4:5], v[60:61]
	s_waitcnt lgkmcnt(0)
	v_pk_mul_f32 v[0:1], v[0:1], v[178:179]
	v_pk_mul_f32 v[28:29], v[28:29], v[52:53]
	v_pk_mul_f32 v[24:25], v[24:25], v[56:57]
	v_pk_mul_f32 v[20:21], v[20:21], v[60:61]
	v_pk_mul_f32 v[14:15], v[14:15], v[54:55]
	v_pk_mul_f32 v[10:11], v[10:11], v[58:59]
	v_pk_mul_f32 v[6:7], v[6:7], v[62:63]
	v_pk_mul_f32 v[2:3], v[2:3], v[180:181]
	v_pk_mul_f32 v[30:31], v[30:31], v[54:55]
	v_pk_mul_f32 v[26:27], v[26:27], v[58:59]
	v_pk_mul_f32 v[22:23], v[22:23], v[62:63]
	v_pk_mul_f32 v[18:19], v[18:19], v[180:181]
	v_pk_mul_f32 v[16:17], v[16:17], v[178:179]
